# v3 + latent scan step: k^T fragments for the state update prefetched at step start / double-buffered (v234-249)
# speedup vs baseline: 1.0004x; 1.0004x over previous
.LBB0_320:
	v_add_u32_e32 v234, v206, v209
	v_add_u32_e32 v242, 0x5000, v234
	v_add_u32_e32 v234, 0x4800, v234
	ds_read2_b64 v[238:241], v234 offset0:8 offset1:12
	ds_read2_b64 v[234:237], v234 offset1:4
	ds_read2_b64 v[246:249], v242 offset0:40 offset1:44
	ds_read2_b64 v[242:245], v242 offset0:32 offset1:36
	v_add_u32_e32 v3, 0xb000, v205
	ds_read_b128 v[56:59], v204 offset:45056
	ds_read2_b32 v[166:167], v3 offset1:16
	ds_read_b128 v[52:55], v204 offset:45120
	ds_read_b128 v[48:51], v204 offset:45184
	ds_read2_b32 v[160:161], v3 offset0:32 offset1:48
	ds_read_b128 v[44:47], v204 offset:45248
	ds_read_b32 v220, v2 offset:45308
	ds_read_b128 v[74:77], v208 offset:27648
	ds_read_b128 v[78:81], v208 offset:28672
	v_cvt_pk_bf16_f32 v64, v24, v25
	v_cvt_pk_bf16_f32 v65, v26, v27
	v_cvt_pk_bf16_f32 v66, v4, v5
	v_cvt_pk_bf16_f32 v67, v6, v7
	v_cvt_pk_bf16_f32 v60, v8, v9
	v_cvt_pk_bf16_f32 v61, v10, v11
	s_waitcnt lgkmcnt(1)
	v_mfma_f32_16x16x32_bf16 v[74:77], v[74:77], v[64:67], 0
	v_cvt_pk_bf16_f32 v62, v12, v13
	v_cvt_pk_bf16_f32 v63, v14, v15
	s_mov_b32 s0, 0x5040100
	v_readlane_b32 s84, v254, 26
	s_waitcnt lgkmcnt(0)
	v_mfma_f32_16x16x32_bf16 v[74:77], v[78:81], v[60:63], v[74:77]
	s_waitcnt vmcnt(13)
	v_lshlrev_b32_e32 v78, 16, v72
	v_and_b32_e32 v79, 0xffff0000, v72
	v_lshlrev_b32_e32 v72, 16, v73
	v_and_b32_e32 v73, 0xffff0000, v73
	v_readlane_b32 s86, v254, 28
	s_nop 1
	v_pk_add_f32 v[158:159], v[78:79], v[74:75] neg_lo:[0,1] neg_hi:[0,1]
	v_pk_add_f32 v[156:157], v[72:73], v[76:77] neg_lo:[0,1] neg_hi:[0,1]
	ds_read_b128 v[72:75], v208 offset:29696
	ds_read_b128 v[76:79], v208 offset:30720
	s_waitcnt lgkmcnt(1)
	v_mfma_f32_16x16x32_bf16 v[72:75], v[72:75], v[64:67], 0
	v_readlane_b32 s87, v254, 29
	v_readlane_b32 s85, v254, 27
	v_add_u32_e32 v191, v213, v211
	s_waitcnt lgkmcnt(0)
	v_mfma_f32_16x16x32_bf16 v[72:75], v[76:79], v[60:63], v[72:75]
	s_waitcnt vmcnt(12)
	v_lshlrev_b32_e32 v76, 16, v70
	v_and_b32_e32 v77, 0xffff0000, v70
	v_lshlrev_b32_e32 v70, 16, v71
	v_and_b32_e32 v71, 0xffff0000, v71
	v_mov_b64_e32 v[110:111], s[86:87]
	s_nop 1
	v_pk_add_f32 v[154:155], v[76:77], v[72:73] neg_lo:[0,1] neg_hi:[0,1]
	v_pk_add_f32 v[150:151], v[70:71], v[74:75] neg_lo:[0,1] neg_hi:[0,1]
	ds_read_b128 v[70:73], v208 offset:31744
	ds_read_b128 v[74:77], v208 offset:32768
	s_waitcnt lgkmcnt(1)
	v_mfma_f32_16x16x32_bf16 v[70:73], v[70:73], v[64:67], 0
	v_mov_b64_e32 v[108:109], s[84:85]
	s_add_i32 s67, s67, -1
	s_mov_b64 s[80:81], 0
	s_waitcnt lgkmcnt(0)
	v_mfma_f32_16x16x32_bf16 v[70:73], v[74:77], v[60:63], v[70:73]
	s_waitcnt vmcnt(11)
	v_lshlrev_b32_e32 v74, 16, v68
	v_and_b32_e32 v75, 0xffff0000, v68
	v_lshlrev_b32_e32 v68, 16, v69
	v_and_b32_e32 v69, 0xffff0000, v69
	s_nop 2
	v_pk_add_f32 v[152:153], v[74:75], v[70:71] neg_lo:[0,1] neg_hi:[0,1]
	v_pk_add_f32 v[148:149], v[68:69], v[72:73] neg_lo:[0,1] neg_hi:[0,1]
	ds_read_b128 v[68:71], v208 offset:33792
	ds_read_b128 v[72:75], v208 offset:34816
	s_waitcnt lgkmcnt(1)
	v_mfma_f32_16x16x32_bf16 v[68:71], v[68:71], v[64:67], 0
	s_waitcnt lgkmcnt(0)
	v_mfma_f32_16x16x32_bf16 v[68:71], v[72:75], v[60:63], v[68:71]
	s_waitcnt vmcnt(10)
	v_lshlrev_b32_e32 v72, 16, v0
	v_and_b32_e32 v73, 0xffff0000, v0
	v_lshlrev_b32_e32 v0, 16, v1
	v_and_b32_e32 v1, 0xffff0000, v1
	v_cvt_pk_bf16_f32 v74, v154, v155
	s_nop 1
	v_pk_add_f32 v[162:163], v[0:1], v[70:71] neg_lo:[0,1] neg_hi:[0,1]
	v_add_u32_e32 v0, v204, v209
	ds_read_b128 v[100:103], v0 offset:9216
	ds_read_b128 v[104:107], v0 offset:9280
	ds_read_b128 v[92:95], v0 offset:11520
	ds_read_b128 v[96:99], v0 offset:11584
	ds_read_b128 v[84:87], v0 offset:13824
	ds_read_b128 v[88:91], v0 offset:13888
	ds_read_b128 v[76:79], v0 offset:16128
	ds_read_b128 v[80:83], v0 offset:16192
	ds_read_b128 v[222:225], v210 offset:64
	ds_read_b128 v[226:229], v210
	s_waitcnt lgkmcnt(0)
	v_mfma_f32_16x16x32_bf16 v[226:229], v[100:103], v[226:229], 0
	v_sub_f32_e32 v0, v166, v56
	v_mul_f32_e32 v0, 0x3fb8aa3b, v0
	v_exp_f32_e32 v0, v0
	v_mfma_f32_16x16x32_bf16 v[222:225], v[104:107], v[222:225], v[226:229]
	v_sub_f32_e32 v1, v166, v59
	v_mul_f32_e32 v1, 0x3fb8aa3b, v1
	v_exp_f32_e32 v1, v1
	v_pk_add_f32 v[164:165], v[72:73], v[68:69] neg_lo:[0,1] neg_hi:[0,1]
	v_cvt_pk_bf16_f32 v72, v158, v159
	s_nop 2
	v_mul_f32_e32 v0, v0, v222
	v_cndmask_b32_e64 v3, v0, 0, s[40:41]
	v_sub_f32_e32 v0, v166, v57
	v_mul_f32_e32 v0, 0x3fb8aa3b, v0
	v_exp_f32_e32 v0, v0
	v_cvt_pk_bf16_f32 v73, v156, v157
	v_cvt_pk_bf16_f32 v75, v150, v151
	v_cvt_pk_bf16_f32 v68, v152, v153
	v_mul_f32_e32 v0, v0, v223
	v_cndmask_b32_e64 v190, 0, v0, s[42:43]
	v_sub_f32_e32 v0, v166, v58
	v_mul_f32_e32 v0, 0x3fb8aa3b, v0
	v_exp_f32_e32 v0, v0
	v_add_u32_e32 v166, v210, v211
	ds_read2_b64 v[230:233], v166 offset0:8 offset1:12
	v_cvt_pk_bf16_f32 v69, v148, v149
	v_pk_mul_f32 v[188:189], v[0:1], v[224:225]
	ds_read2_b64 v[222:225], v166 offset1:4
	v_cvt_pk_bf16_f32 v1, v188, v189
	v_cvt_pk_bf16_f32 v0, v3, v190
	v_cndmask_b32_e64 v3, v1, 0, s[46:47]
	v_lshrrev_b32_e32 v1, 16, v1
	v_cndmask_b32_e64 v1, v1, 0, s[44:45]
	v_perm_b32 v1, v1, v3, s0
	v_mov_b32_e32 v3, v2
	s_waitcnt lgkmcnt(0)
	v_mfma_f32_16x16x32_bf16 v[222:225], v[222:225], v[64:67], 0
	v_cvt_pk_bf16_f32 v70, v164, v165
	v_cvt_pk_bf16_f32 v71, v162, v163
	v_sub_f32_e32 v166, v167, v53
	v_mfma_f32_16x16x32_bf16 v[226:229], v[0:3], v[72:75], 0
	v_mul_f32_e32 v0, 0x3fb8aa3b, v56
	v_exp_f32_e32 v0, v0
	v_mul_f32_e32 v166, 0x3fb8aa3b, v166
	v_mfma_f32_16x16x32_bf16 v[222:225], v[230:233], v[60:63], v[222:225]
	v_exp_f32_e32 v166, v166
	v_sub_f32_e32 v3, v167, v58
	v_mul_f32_e32 v3, 0x3fb8aa3b, v3
	v_mfma_f32_16x16x32_bf16 v[226:229], v[108:111], v[68:71], v[226:229]
	v_exp_f32_e32 v188, v3
	v_sub_f32_e32 v3, v167, v59
	v_mul_f32_e32 v3, 0x3fb8aa3b, v3
	v_sub_f32_e32 v1, v167, v57
	v_exp_f32_e32 v189, v3
	s_nop 2
	v_fma_f32 v0, v0, v222, v226
	v_cvt_pk_bf16_f32 v0, v0, s0
	ds_write_b16 v212, v0 offset:35840
	v_mul_f32_e32 v0, 0x3fb8aa3b, v57
	v_exp_f32_e32 v0, v0
	v_sub_f32_e32 v3, v167, v52
	v_mul_f32_e32 v1, 0x3fb8aa3b, v1
	v_mul_f32_e32 v3, 0x3fb8aa3b, v3
	v_fma_f32 v0, v0, v223, v227
	v_cvt_pk_bf16_f32 v0, v0, s0
	ds_write_b16 v212, v0 offset:35984
	v_mul_f32_e32 v0, 0x3fb8aa3b, v58
	v_exp_f32_e32 v0, v0
	v_exp_f32_e32 v1, v1
	v_exp_f32_e32 v3, v3
	v_fma_f32 v0, v0, v224, v228
	v_cvt_pk_bf16_f32 v0, v0, s0
	ds_write_b16 v212, v0 offset:36128
	v_mul_f32_e32 v0, 0x3fb8aa3b, v59
	v_exp_f32_e32 v0, v0
	s_nop 0
	v_fmac_f32_e32 v229, v0, v225
	v_cvt_pk_bf16_f32 v0, v229, s0
	ds_write_b16 v212, v0 offset:36272
	ds_read_b128 v[222:225], v213
	ds_read_b128 v[226:229], v213 offset:64
	s_waitcnt lgkmcnt(1)
	v_mfma_f32_16x16x32_bf16 v[230:233], v[100:103], v[222:225], 0
	v_sub_f32_e32 v0, v167, v56
	v_mul_f32_e32 v0, 0x3fb8aa3b, v0
	v_exp_f32_e32 v0, v0
	v_mfma_f32_16x16x32_bf16 v[222:225], v[92:95], v[222:225], 0
	s_waitcnt lgkmcnt(0)
	v_mfma_f32_16x16x32_bf16 v[222:225], v[96:99], v[226:229], v[222:225]
	v_mfma_f32_16x16x32_bf16 v[230:233], v[104:107], v[226:229], v[230:233]
	s_nop 6
	v_mul_f32_e32 v166, v166, v223
	v_cndmask_b32_e64 v190, v166, 0, s[48:49]
	v_sub_f32_e32 v166, v167, v54
	v_sub_f32_e32 v167, v167, v55
	v_mul_f32_e32 v166, 0x3fb8aa3b, v166
	v_mul_f32_e32 v167, 0x3fb8aa3b, v167
	v_exp_f32_e32 v166, v166
	v_exp_f32_e32 v167, v167
	v_pk_mul_f32 v[0:1], v[0:1], v[230:231]
	v_mul_f32_e32 v3, v3, v222
	v_cvt_pk_bf16_f32 v226, v0, v1
	v_pk_mul_f32 v[166:167], v[166:167], v[224:225]
	ds_read2_b64 v[222:225], v191 offset1:4
	v_cvt_pk_bf16_f32 v0, v166, v167
	v_cndmask_b32_e64 v1, v0, 0, s[52:53]
	v_lshrrev_b32_e32 v0, 16, v0
	v_pk_mul_f32 v[188:189], v[188:189], v[232:233]
	v_cndmask_b32_e64 v3, v3, 0, s[40:41]
	v_cndmask_b32_e64 v0, v0, 0, s[50:51]
	v_cvt_pk_bf16_f32 v227, v188, v189
	v_cvt_pk_bf16_f32 v228, v3, v190
	v_perm_b32 v229, v0, v1, s0
	ds_read2_b64 v[230:233], v191 offset0:8 offset1:12
	s_waitcnt lgkmcnt(1)
	v_mfma_f32_16x16x32_bf16 v[222:225], v[222:225], v[64:67], 0
	v_mul_f32_e32 v0, 0x3fb8aa3b, v52
	v_exp_f32_e32 v0, v0
	v_sub_f32_e32 v3, v160, v58
	v_mfma_f32_16x16x32_bf16 v[226:229], v[226:229], v[72:75], 0
	v_mul_f32_e32 v3, 0x3fb8aa3b, v3
	v_exp_f32_e32 v166, v3
	v_sub_f32_e32 v3, v160, v59
	s_waitcnt lgkmcnt(0)
	v_mfma_f32_16x16x32_bf16 v[222:225], v[230:233], v[60:63], v[222:225]
	v_mul_f32_e32 v3, 0x3fb8aa3b, v3
	v_sub_f32_e32 v1, v160, v57
	v_exp_f32_e32 v167, v3
	v_mfma_f32_16x16x32_bf16 v[108:111], v[108:111], v[68:71], v[226:229]
	v_sub_f32_e32 v3, v160, v52
	v_mul_f32_e32 v1, 0x3fb8aa3b, v1
	v_mul_f32_e32 v3, 0x3fb8aa3b, v3
	v_exp_f32_e32 v1, v1
	v_exp_f32_e32 v188, v3
	s_nop 2
	v_fma_f32 v0, v0, v222, v108
	v_cvt_pk_bf16_f32 v0, v0, s0
	ds_write_b16 v212, v0 offset:38144
	v_mul_f32_e32 v0, 0x3fb8aa3b, v53
	v_exp_f32_e32 v0, v0
	v_sub_f32_e32 v3, v160, v53
	v_mul_f32_e32 v3, 0x3fb8aa3b, v3
	v_exp_f32_e32 v189, v3
	v_fma_f32 v0, v0, v223, v109
	v_cvt_pk_bf16_f32 v0, v0, s0
	ds_write_b16 v212, v0 offset:38288
	v_mul_f32_e32 v0, 0x3fb8aa3b, v54
	v_exp_f32_e32 v0, v0
	v_sub_f32_e32 v3, v160, v54
	v_mul_f32_e32 v3, 0x3fb8aa3b, v3
	v_exp_f32_e32 v190, v3
	v_fma_f32 v0, v0, v224, v110
	v_cvt_pk_bf16_f32 v0, v0, s0
	ds_write_b16 v212, v0 offset:38432
	v_mul_f32_e32 v0, 0x3fb8aa3b, v55
	v_exp_f32_e32 v0, v0
	v_sub_f32_e32 v3, v160, v55
	v_mul_f32_e32 v3, 0x3fb8aa3b, v3
	v_exp_f32_e32 v191, v3
	v_fmac_f32_e32 v111, v0, v225
	v_cvt_pk_bf16_f32 v0, v111, s0
	ds_write_b16 v212, v0 offset:38576
	ds_read_b128 v[108:111], v214
	ds_read_b128 v[222:225], v214 offset:64
	s_waitcnt lgkmcnt(1)
	v_mfma_f32_16x16x32_bf16 v[226:229], v[100:103], v[108:111], 0
	v_sub_f32_e32 v0, v160, v56
	v_mul_f32_e32 v0, 0x3fb8aa3b, v0
	v_exp_f32_e32 v0, v0
	s_waitcnt lgkmcnt(0)
	v_mfma_f32_16x16x32_bf16 v[226:229], v[104:107], v[222:225], v[226:229]
	v_sub_f32_e32 v3, v160, v48
	v_mul_f32_e32 v3, 0x3fb8aa3b, v3
	v_exp_f32_e32 v3, v3
	s_nop 4
	v_pk_mul_f32 v[0:1], v[0:1], v[226:227]
	v_pk_mul_f32 v[166:167], v[166:167], v[228:229]
	v_mfma_f32_16x16x32_bf16 v[226:229], v[92:95], v[108:111], 0
	v_mfma_f32_16x16x32_bf16 v[108:111], v[84:87], v[108:111], 0
	v_mfma_f32_16x16x32_bf16 v[108:111], v[88:91], v[222:225], v[108:111]
	v_mfma_f32_16x16x32_bf16 v[226:229], v[96:99], v[222:225], v[226:229]
	v_cvt_pk_bf16_f32 v222, v0, v1
	s_nop 5
	v_mul_f32_e32 v3, v3, v108
	v_sub_f32_e32 v108, v160, v49
	v_mul_f32_e32 v108, 0x3fb8aa3b, v108
	v_exp_f32_e32 v108, v108
	v_pk_mul_f32 v[188:189], v[188:189], v[226:227]
	v_pk_mul_f32 v[190:191], v[190:191], v[228:229]
	v_cvt_pk_bf16_f32 v223, v166, v167
	v_mul_f32_e32 v108, v108, v109
	v_cndmask_b32_e64 v221, v108, 0, s[54:55]
	v_sub_f32_e32 v108, v160, v50
	v_sub_f32_e32 v109, v160, v51
	v_mul_f32_e32 v108, 0x3fb8aa3b, v108
	v_mul_f32_e32 v109, 0x3fb8aa3b, v109
	v_exp_f32_e32 v108, v108
	v_exp_f32_e32 v109, v109
	v_add_u32_e32 v160, v214, v211
	v_cvt_pk_bf16_f32 v224, v188, v189
	v_cvt_pk_bf16_f32 v225, v190, v191
	v_pk_mul_f32 v[230:231], v[108:109], v[110:111]
	ds_read2_b64 v[108:111], v160 offset1:4
	v_cndmask_b32_e64 v3, v3, 0, s[40:41]
	ds_read2_b64 v[226:229], v160 offset0:8 offset1:12
	v_cvt_pk_bf16_f32 v1, v230, v231
	v_cvt_pk_bf16_f32 v0, v3, v221
	v_cndmask_b32_e64 v3, v1, 0, s[58:59]
	v_lshrrev_b32_e32 v1, 16, v1
	v_cndmask_b32_e64 v1, v1, 0, s[56:57]
	v_perm_b32 v1, v1, v3, s0
	v_mov_b32_e32 v3, v2
	v_mfma_f32_16x16x32_bf16 v[222:225], v[222:225], v[72:75], 0
	s_waitcnt lgkmcnt(1)
	v_mfma_f32_16x16x32_bf16 v[108:111], v[108:111], v[64:67], 0
	v_mfma_f32_16x16x32_bf16 v[222:225], v[0:3], v[68:71], v[222:225]
	v_mul_f32_e32 v0, 0x3fb8aa3b, v48
	v_exp_f32_e32 v0, v0
	v_sub_f32_e32 v1, v161, v57
	s_waitcnt lgkmcnt(0)
	v_mfma_f32_16x16x32_bf16 v[108:111], v[226:229], v[60:63], v[108:111]
	v_mul_f32_e32 v1, 0x3fb8aa3b, v1
	v_exp_f32_e32 v1, v1
	v_sub_f32_e32 v3, v161, v58
	v_mul_f32_e32 v3, 0x3fb8aa3b, v3
	s_nop 3
	v_fma_f32 v0, v0, v108, v222
	v_cvt_pk_bf16_f32 v0, v0, s0
	ds_write_b16 v212, v0 offset:40448
	v_mul_f32_e32 v0, 0x3fb8aa3b, v49
	v_exp_f32_e32 v0, v0
	s_nop 0
	v_fma_f32 v0, v0, v109, v223
	v_cvt_pk_bf16_f32 v0, v0, s0
	ds_write_b16 v212, v0 offset:40592
	v_mul_f32_e32 v0, 0x3fb8aa3b, v50
	v_exp_f32_e32 v0, v0
	s_nop 0
	v_fma_f32 v0, v0, v110, v224
	v_cvt_pk_bf16_f32 v0, v0, s0
	ds_write_b16 v212, v0 offset:40736
	v_mul_f32_e32 v0, 0x3fb8aa3b, v51
	v_exp_f32_e32 v0, v0
	s_nop 0
	v_fmac_f32_e32 v225, v0, v111
	v_cvt_pk_bf16_f32 v0, v225, s0
	ds_write_b16 v212, v0 offset:40880
	ds_read_b128 v[108:111], v215
	ds_read_b128 v[222:225], v215 offset:64
	s_waitcnt lgkmcnt(1)
	v_mfma_f32_16x16x32_bf16 v[100:103], v[100:103], v[108:111], 0
	v_sub_f32_e32 v0, v161, v56
	v_mul_f32_e32 v0, 0x3fb8aa3b, v0
	v_exp_f32_e32 v0, v0
	s_waitcnt lgkmcnt(0)
	v_mfma_f32_16x16x32_bf16 v[100:103], v[104:107], v[222:225], v[100:103]
	v_mfma_f32_16x16x32_bf16 v[92:95], v[92:95], v[108:111], 0
	v_mfma_f32_16x16x32_bf16 v[92:95], v[96:99], v[222:225], v[92:95]
	s_nop 5
	v_mul_f32_e64 v0, v0, v100
	v_mul_f32_e64 v1, v1, v101
	v_exp_f32_e32 v100, v3
	v_sub_f32_e32 v3, v161, v59
	v_mul_f32_e32 v3, 0x3fb8aa3b, v3
	v_exp_f32_e32 v101, v3
	v_sub_f32_e32 v3, v161, v52
	v_mul_f32_e32 v3, 0x3fb8aa3b, v3
	v_exp_f32_e32 v96, v3
	v_sub_f32_e32 v3, v161, v53
	v_mul_f32_e32 v3, 0x3fb8aa3b, v3
	v_exp_f32_e32 v97, v3
	v_sub_f32_e32 v3, v161, v54
	v_mul_f32_e32 v3, 0x3fb8aa3b, v3
	v_mfma_f32_16x16x32_bf16 v[84:87], v[84:87], v[108:111], 0
	v_mul_f32_e64 v92, v96, v92
	v_mul_f32_e64 v93, v97, v93
	v_exp_f32_e32 v96, v3
	v_sub_f32_e32 v3, v161, v55
	v_mul_f32_e32 v3, 0x3fb8aa3b, v3
	v_exp_f32_e32 v97, v3
	v_sub_f32_e32 v3, v161, v48
	v_mul_f32_e32 v3, 0x3fb8aa3b, v3
	v_mfma_f32_16x16x32_bf16 v[84:87], v[88:91], v[222:225], v[84:87]
	v_exp_f32_e32 v88, v3
	v_sub_f32_e32 v3, v161, v49
	v_mul_f32_e32 v3, 0x3fb8aa3b, v3
	v_exp_f32_e32 v89, v3
	v_sub_f32_e32 v3, v161, v50
	v_mul_f32_e32 v3, 0x3fb8aa3b, v3
	v_mfma_f32_16x16x32_bf16 v[76:79], v[76:79], v[108:111], 0
	s_nop 0
	v_mul_f32_e64 v84, v88, v84
	v_mul_f32_e64 v85, v89, v85
	v_exp_f32_e32 v88, v3
	v_sub_f32_e32 v3, v161, v51
	v_mul_f32_e32 v3, 0x3fb8aa3b, v3
	v_exp_f32_e32 v89, v3
	v_sub_f32_e32 v3, v161, v44
	v_mul_f32_e32 v3, 0x3fb8aa3b, v3
	v_mfma_f32_16x16x32_bf16 v[76:79], v[80:83], v[222:225], v[76:79]
	v_exp_f32_e32 v3, v3
	v_add_u32_e32 v83, v215, v211
	v_pk_mul_f32 v[100:101], v[100:101], v[102:103]
	v_pk_mul_f32 v[94:95], v[96:97], v[94:95]
	v_pk_mul_f32 v[86:87], v[88:89], v[86:87]
	s_nop 2
	v_mul_f32_e32 v3, v3, v76
	v_sub_f32_e32 v76, v161, v45
	v_mul_f32_e32 v76, 0x3fb8aa3b, v76
	v_exp_f32_e32 v76, v76
	v_cndmask_b32_e64 v3, v3, 0, s[40:41]
	v_mul_f32_e32 v76, v76, v77
	v_cndmask_b32_e64 v82, v76, 0, s[60:61]
	v_sub_f32_e32 v76, v161, v46
	v_sub_f32_e32 v77, v161, v47
	v_mul_f32_e32 v76, 0x3fb8aa3b, v76
	v_mul_f32_e32 v77, 0x3fb8aa3b, v77
	v_exp_f32_e32 v76, v76
	v_exp_f32_e32 v77, v77
	s_nop 0
	v_pk_mul_f32 v[80:81], v[76:77], v[78:79]
	ds_read2_b64 v[76:79], v83 offset1:4
	s_waitcnt lgkmcnt(0)
	v_mfma_f32_16x16x32_bf16 v[64:67], v[76:79], v[64:67], 0
	v_cvt_pk_bf16_f32 v76, v0, v1
	v_cvt_pk_bf16_f32 v77, v100, v101
	v_cvt_pk_bf16_f32 v78, v92, v93
	v_cvt_pk_bf16_f32 v79, v94, v95
	v_cvt_pk_bf16_f32 v0, v80, v81
	v_cndmask_b32_e64 v1, v0, 0, s[64:65]
	v_mfma_f32_16x16x32_bf16 v[72:75], v[76:79], v[72:75], 0
	ds_read2_b64 v[76:79], v83 offset0:8 offset1:12
	v_lshrrev_b32_e32 v0, 16, v0
	v_cndmask_b32_e64 v0, v0, 0, s[62:63]
	s_waitcnt lgkmcnt(0)
	v_mfma_f32_16x16x32_bf16 v[60:63], v[76:79], v[60:63], v[64:67]
	s_nop 2
	v_cvt_pk_bf16_f32 v64, v84, v85
	v_cvt_pk_bf16_f32 v65, v86, v87
	v_cvt_pk_bf16_f32 v66, v3, v82
	v_perm_b32 v67, v0, v1, s0
	v_mul_f32_e32 v0, 0x3fb8aa3b, v44
	v_exp_f32_e32 v0, v0
	v_mfma_f32_16x16x32_bf16 v[64:67], v[64:67], v[68:71], v[72:75]
	v_sub_f32_e32 v3, v220, v58
	v_mul_f32_e32 v3, 0x3fb8aa3b, v3
	v_sub_f32_e32 v1, v220, v57
	s_nop 4
	v_fma_f32 v0, v0, v60, v64
	v_cvt_pk_bf16_f32 v0, v0, s0
	ds_write_b16 v212, v0 offset:42752
	v_mul_f32_e32 v0, 0x3fb8aa3b, v45
	v_exp_f32_e32 v0, v0
	v_mul_f32_e32 v1, 0x3fb8aa3b, v1
	v_exp_f32_e32 v1, v1
	s_waitcnt vmcnt(1)
	v_mov_b64_e32 v[68:69], v[144:145]
	v_fma_f32 v0, v0, v61, v65
	v_cvt_pk_bf16_f32 v0, v0, s0
	ds_write_b16 v216, v0 offset:35840
	v_mul_f32_e32 v0, 0x3fb8aa3b, v46
	v_exp_f32_e32 v0, v0
	v_mov_b64_e32 v[70:71], v[142:143]
	v_mov_b64_e32 v[72:73], v[140:141]
	v_fma_f32 v0, v0, v62, v66
	v_cvt_pk_bf16_f32 v0, v0, s0
	ds_write_b16 v217, v0 offset:35840
	v_mul_f32_e32 v0, 0x3fb8aa3b, v47
	v_exp_f32_e32 v0, v0
	s_nop 0
	v_fmac_f32_e32 v67, v0, v63
	v_cvt_pk_bf16_f32 v0, v67, s0
	ds_write_b16 v218, v0 offset:35840
	v_sub_f32_e32 v0, v220, v56
	v_exp_f32_e32 v56, v3
	v_sub_f32_e32 v3, v220, v59
	v_mul_f32_e32 v3, 0x3fb8aa3b, v3
	v_exp_f32_e32 v57, v3
	v_sub_f32_e32 v3, v220, v52
	v_mul_f32_e32 v3, 0x3fb8aa3b, v3
	v_exp_f32_e32 v52, v3
	v_sub_f32_e32 v3, v220, v53
	v_mul_f32_e32 v3, 0x3fb8aa3b, v3
	v_exp_f32_e32 v53, v3
	v_sub_f32_e32 v3, v220, v54
	v_mul_f32_e32 v3, 0x3fb8aa3b, v3
	v_exp_f32_e32 v54, v3
	v_sub_f32_e32 v3, v220, v55
	v_mul_f32_e32 v3, 0x3fb8aa3b, v3
	v_exp_f32_e32 v55, v3
	v_sub_f32_e32 v3, v220, v48
	v_mul_f32_e32 v3, 0x3fb8aa3b, v3
	v_exp_f32_e32 v48, v3
	v_sub_f32_e32 v3, v220, v49
	v_mul_f32_e32 v3, 0x3fb8aa3b, v3
	v_exp_f32_e32 v49, v3
	v_sub_f32_e32 v3, v220, v50
	v_mul_f32_e32 v3, 0x3fb8aa3b, v3
	v_exp_f32_e32 v50, v3
	v_sub_f32_e32 v3, v220, v51
	v_mul_f32_e32 v3, 0x3fb8aa3b, v3
	v_exp_f32_e32 v51, v3
	v_sub_f32_e32 v3, v220, v44
	v_mul_f32_e32 v3, 0x3fb8aa3b, v3
	v_exp_f32_e32 v44, v3
	v_sub_f32_e32 v3, v220, v45
	v_mul_f32_e32 v3, 0x3fb8aa3b, v3
	v_exp_f32_e32 v45, v3
	v_sub_f32_e32 v3, v220, v46
	v_mul_f32_e32 v3, 0x3fb8aa3b, v3
	v_mul_f32_e32 v0, 0x3fb8aa3b, v0
	v_pk_mul_f32 v[58:59], v[44:45], v[164:165]
	v_exp_f32_e32 v44, v3
	v_sub_f32_e32 v3, v220, v47
	v_exp_f32_e32 v0, v0
	v_mul_f32_e32 v3, 0x3fb8aa3b, v3
	v_exp_f32_e32 v45, v3
	v_pk_mul_f32 v[52:53], v[52:53], v[154:155]
	v_pk_mul_f32 v[0:1], v[0:1], v[158:159]
	v_pk_mul_f32 v[54:55], v[54:55], v[150:151]
	v_pk_mul_f32 v[60:61], v[44:45], v[162:163]
	v_cvt_pk_bf16_f32 v44, v0, v1
	v_mul_f32_e32 v0, 0x3fb8aa3b, v220
	v_exp_f32_e32 v0, v0
	v_cvt_pk_bf16_f32 v46, v52, v53
	v_cvt_pk_bf16_f32 v47, v54, v55
	v_pk_mul_f32 v[56:57], v[56:57], v[156:157]
	v_pk_mul_f32 v[26:27], v[26:27], v[0:1] op_sel_hi:[1,0]
	v_pk_mul_f32 v[24:25], v[24:25], v[0:1] op_sel_hi:[1,0]
	v_add_u32_e32 v1, v206, v209
	v_add_u32_e32 v3, 0x5800, v1
	v_cvt_pk_bf16_f32 v45, v56, v57
	v_pk_mul_f32 v[48:49], v[48:49], v[152:153]
	v_pk_mul_f32 v[50:51], v[50:51], v[148:149]
	s_waitcnt lgkmcnt(0)
	v_mfma_f32_16x16x32_bf16 v[24:27], v[234:237], v[44:47], v[24:27]
	ds_read2_b64 v[234:237], v3 offset0:64 offset1:68
	v_cvt_pk_bf16_f32 v48, v48, v49
	v_cvt_pk_bf16_f32 v49, v50, v51
	v_cvt_pk_bf16_f32 v50, v58, v59
	v_cvt_pk_bf16_f32 v51, v60, v61
	v_pk_mul_f32 v[6:7], v[6:7], v[0:1] op_sel_hi:[1,0]
	v_pk_mul_f32 v[4:5], v[4:5], v[0:1] op_sel_hi:[1,0]
	v_mfma_f32_16x16x32_bf16 v[24:27], v[238:241], v[48:51], v[24:27]
	ds_read2_b64 v[238:241], v3 offset0:72 offset1:76
	v_pk_mul_f32 v[10:11], v[10:11], v[0:1] op_sel_hi:[1,0]
	v_pk_mul_f32 v[8:9], v[8:9], v[0:1] op_sel_hi:[1,0]
	v_mfma_f32_16x16x32_bf16 v[4:7], v[242:245], v[44:47], v[4:7]
	v_pk_mul_f32 v[14:15], v[14:15], v[0:1] op_sel_hi:[1,0]
	v_pk_mul_f32 v[12:13], v[12:13], v[0:1] op_sel_hi:[1,0]
	v_add_u32_e32 v0, 0x6000, v1
	ds_read2_b64 v[242:245], v0 offset0:96 offset1:100
	v_mfma_f32_16x16x32_bf16 v[4:7], v[246:249], v[48:51], v[4:7]
	ds_read2_b64 v[246:249], v0 offset0:104 offset1:108
	s_waitcnt lgkmcnt(3)
	v_mfma_f32_16x16x32_bf16 v[8:11], v[234:237], v[44:47], v[8:11]
	s_waitcnt lgkmcnt(2)
	v_mfma_f32_16x16x32_bf16 v[8:11], v[238:241], v[48:51], v[8:11]
	s_waitcnt lgkmcnt(1)
	v_mfma_f32_16x16x32_bf16 v[12:15], v[242:245], v[44:47], v[12:15]
	s_waitcnt vmcnt(0)
	v_mov_b64_e32 v[0:1], v[146:147]
	s_waitcnt lgkmcnt(0)
	v_mfma_f32_16x16x32_bf16 v[12:15], v[246:249], v[48:51], v[12:15]
